# S8 context-row tiles split into row halves so all 32 workgroups of an XCD work (was 16 of 32)
# speedup vs baseline: 1.0111x; 1.0009x over previous
; #define LAS __attribute__((address_space(3)))
; template <int MODE>
; DEV void cgemm_tile(const Fr& F, const bf16_t* A, const bf16_t* Bt, int K, int rb, int cb, bf16_t* O, int ldc) {
;     LAS float* part = (LAS float*)F.lds;
;     const int w = F.wave, fr = F.lane & 15, fq = F.lane >> 4;
;     const int arow0 = (rb >> 2) * RPB + (rb & 3) * 64;
;     int brow[4];
; #pragma unroll
;     for (int ni = 0; ni < 4; ++ni) {
;         if (MODE == 0) brow[ni] = cb * 64 + ni * 16;
;         else { const int j = cb * 32 + (ni & 1) * 16; brow[ni] = (j >> 7) * 256 + (ni >> 1) * 128 + (j & 127); }
;     }
;     const int kslice = K >> 3, steps = kslice >> 5;
;     const bf16_t* ap = A + (size_t)(arow0 + fr) * K + w * kslice + 8 * fq;
;     const bf16_t* bp = Bt + (size_t)fr * K + w * kslice + 8 * fq;
.LBB0_1381:
	v_mov_b32_e32 v1, v188
	s_and_b64 vcc, exec, s[38:39]
	v_readfirstlane_b32 s0, v1
	s_cbranch_vccnz .LBB0_1397
	v_and_b32_e32 v141, 63, v1
	s_ashr_i32 s15, s0, 6
	s_and_b64 vcc, exec, s[74:75]
	s_mov_b64 s[0:1], -1
	s_cbranch_vccnz .LBB0_1387
	v_and_b32_e32 v3, 15, v1
	s_lshl_b32 s0, s15, 14
	v_lshrrev_b32_e32 v2, 2, v141
	s_waitcnt vmcnt(0)
	v_lshlrev_b32_e32 v9, 2, v3
	s_add_i32 s0, s0, 0
	v_readlane_b32 s2, v242, 31
	v_and_b32_e32 v8, 12, v2
	v_lshl_add_u32 v10, v3, 8, s0
	v_bitop3_b32 v2, v2, v9, 12 bitop3:0x6c
	v_or_b32_e32 v4, s2, v3
	s_mul_i32 s0, s15, 0x160
	v_lshl_add_u32 v176, v2, 2, v10
	s_ashr_i32 s1, s0, 31
	v_mul_u32_u24_e32 v2, 0xb00, v3
	v_mul_u32_u24_e32 v4, 0x1600, v4
	v_mov_b32_e32 v5, v0
	v_lshlrev_b32_e32 v2, 1, v2
	v_mov_b32_e32 v3, v0
	s_lshl_b64 s[0:1], s[0:1], 1
	v_lshl_add_u64 v[4:5], s[78:79], 0, v[4:5]
	v_lshl_add_u64 v[2:3], s[16:17], 0, v[2:3]
	v_lshl_add_u64 v[4:5], v[4:5], 0, s[0:1]
	v_and_b32_e32 v6, 48, v141
	v_mov_b32_e32 v7, v0
	v_lshl_add_u64 v[2:3], v[2:3], 0, s[0:1]
	v_lshl_add_u64 v[90:91], v[4:5], 0, v[6:7]
	s_mov_b64 s[0:1], 0x16000
	v_lshl_add_u64 v[94:95], v[90:91], 0, s[0:1]
	s_mov_b64 s[0:1], 0x2c000
	v_lshl_add_u64 v[96:97], v[90:91], 0, s[0:1]
	s_mov_b64 s[0:1], 0x42000
	v_lshl_add_u64 v[98:99], v[90:91], 0, s[0:1]
	s_mov_b64 s[0:1], 0x16040
	v_lshl_add_u64 v[100:101], v[90:91], 0, s[0:1]
	s_mov_b64 s[0:1], 0x2c040
	v_lshl_add_u64 v[102:103], v[90:91], 0, s[0:1]
	s_mov_b64 s[0:1], 0x42040
	v_lshl_add_u64 v[104:105], v[90:91], 0, s[0:1]
	s_mov_b64 s[0:1], 0x16080
	v_lshl_add_u64 v[106:107], v[90:91], 0, s[0:1]
	s_mov_b64 s[0:1], 0x2c080
	v_lshl_add_u64 v[108:109], v[90:91], 0, s[0:1]
	s_mov_b64 s[0:1], 0x42080
	v_lshl_add_u64 v[110:111], v[90:91], 0, s[0:1]
	s_mov_b64 s[0:1], 0x160c0
	v_lshl_add_u64 v[112:113], v[90:91], 0, s[0:1]
	s_mov_b64 s[0:1], 0x2c0c0
	v_lshl_add_u64 v[114:115], v[90:91], 0, s[0:1]
	s_mov_b64 s[0:1], 0x420c0
	v_lshl_add_u64 v[116:117], v[90:91], 0, s[0:1]
	s_mov_b64 s[0:1], 0x16100
	v_lshl_add_u64 v[118:119], v[90:91], 0, s[0:1]
	s_mov_b64 s[0:1], 0x2c100
	v_lshl_add_u64 v[120:121], v[90:91], 0, s[0:1]
	s_mov_b64 s[0:1], 0x42100
	v_lshl_add_u64 v[122:123], v[90:91], 0, s[0:1]
	s_mov_b64 s[0:1], 0x16140
	v_lshl_add_u64 v[124:125], v[90:91], 0, s[0:1]
	s_mov_b64 s[0:1], 0x2c140
	v_lshl_add_u64 v[126:127], v[90:91], 0, s[0:1]
	s_mov_b64 s[0:1], 0x42140
	v_lshl_add_u64 v[128:129], v[90:91], 0, s[0:1]
	s_mov_b64 s[0:1], 0x16180
	v_lshl_add_u64 v[130:131], v[90:91], 0, s[0:1]
	s_mov_b64 s[0:1], 0x2c180
	v_lshl_add_u64 v[92:93], v[2:3], 0, v[6:7]
	v_lshl_add_u64 v[132:133], v[90:91], 0, s[0:1]
	s_mov_b64 s[0:1], 0x42180
	v_bitop3_b32 v2, v8, v9, 16 bitop3:0x36
	v_lshl_add_u64 v[134:135], v[90:91], 0, s[0:1]
	s_mov_b64 s[0:1], 0x161c0
	v_lshl_add_u32 v177, v2, 2, v10
	v_bitop3_b32 v2, v8, v9, 32 bitop3:0x36
	v_lshl_add_u64 v[136:137], v[90:91], 0, s[0:1]
	s_mov_b64 s[0:1], 0x2c1c0
	v_lshl_add_u32 v178, v2, 2, v10
	v_bitop3_b32 v2, v8, v9, 48 bitop3:0x36
	v_lshl_add_u64 v[138:139], v[90:91], 0, s[0:1]
	s_mov_b64 s[0:1], 0x421c0
	v_lshl_add_u32 v179, v2, 2, v10
	v_ashrrev_i32_e32 v2, 3, v1
	v_lshlrev_b32_e32 v3, 3, v1
	v_lshl_add_u64 v[150:151], v[90:91], 0, s[0:1]
	s_mov_b64 s[0:1], 0x16200
	v_and_b32_e32 v4, 56, v3
	v_lshlrev_b32_e32 v3, 2, v2
	v_lshl_add_u64 v[152:153], v[90:91], 0, s[0:1]
	s_mov_b64 s[0:1], 0x2c200
	v_and_b32_e32 v5, 60, v3
	v_lshl_add_u64 v[154:155], v[90:91], 0, s[0:1]
	s_mov_b64 s[0:1], 0x42200
	v_lshl_add_u32 v6, v2, 8, 0
	v_bitop3_b32 v3, v3, v4, 60 bitop3:0x6c
	v_bitop3_b32 v5, v4, v5, 4 bitop3:0x36
	v_lshl_add_u64 v[156:157], v[90:91], 0, s[0:1]
	s_mov_b64 s[0:1], 0x16240
	v_lshlrev_b32_e32 v3, 2, v3
	v_lshlrev_b32_e32 v5, 2, v5
	v_add_u32_e32 v7, 0x10000, v6
	v_lshl_add_u64 v[158:159], v[90:91], 0, s[0:1]
	s_mov_b64 s[0:1], 0x2c240
	v_add_u32_e32 v182, v7, v3
	v_add_u32_e32 v183, v7, v5
	v_add_u32_e32 v7, 0x14000, v6
	v_lshl_add_u64 v[160:161], v[90:91], 0, s[0:1]
	s_mov_b64 s[0:1], 0x42240
	v_add_u32_e32 v180, v6, v3
	v_add_u32_e32 v181, v6, v5
	v_add_u32_e32 v184, v7, v3
	v_add_u32_e32 v185, v7, v5
	v_add_u32_e32 v7, 0x18000, v6
	v_add_u32_e32 v6, 0x1c000, v6
	v_add_u32_e32 v2, s2, v2
	v_lshl_add_u64 v[162:163], v[90:91], 0, s[0:1]
	s_mov_b64 s[0:1], 0x16280
	v_add_u32_e32 v186, v7, v3
	v_add_u32_e32 v198, v6, v3
	v_ashrrev_i32_e32 v3, 31, v2
	v_lshl_add_u64 v[164:165], v[90:91], 0, s[0:1]
	s_mov_b64 s[0:1], 0x2c280
	v_lshlrev_b64 v[2:3], 11, v[2:3]
	v_lshl_add_u64 v[166:167], v[90:91], 0, s[0:1]
	s_mov_b64 s[0:1], 0x42280
	v_add_u32_e32 v187, v7, v5
	v_add_u32_e32 v199, v6, v5
	v_lshl_add_u64 v[2:3], s[12:13], 0, v[2:3]
	v_lshlrev_b32_e32 v4, 1, v4
	v_mov_b32_e32 v5, v0
	v_lshl_add_u64 v[168:169], v[90:91], 0, s[0:1]
	v_lshl_add_u64 v[170:171], v[2:3], 0, v[4:5]
	v_readlane_b32 s0, v240, 47
	v_readlane_b32 s2, v240, 46
	s_nop 1
	s_lshr_b32 s3, s0, 10
	s_and_b32 s0, s0, 0x3ff
	s_mul_i32 s6, s3, 0x2c000
	s_mov_b32 s7, 0
	s_lshl_b32 s3, s3, 13
	v_lshl_add_u64 v[90:91], v[90:91], 0, s[6:7]
	v_lshl_add_u64 v[94:95], v[94:95], 0, s[6:7]
	v_add_u32_e32 v176, s3, v176
	v_add_u32_e32 v177, s3, v177
	v_add_u32_e32 v178, s3, v178
	v_add_u32_e32 v179, s3, v179
; template <int CH>
; DEV void cg_chunk(f32x4 (&acc)[4][4], const bf16_t* ap, const bf16_t* bp, const int (&brow)[4], int K) {
;     bf16x8 a[CH][4], b[CH][4];
; #pragma unroll
;     for (int c = 0; c < CH; ++c)
; #pragma unroll
;         for (int i = 0; i < 4; ++i) { a[c][i] = *(const bf16x8*)(ap + (size_t)(16 * i) * K + 32 * c); b[c][i] = *(const bf16x8*)(bp + (size_t)brow[i] * K + 32 * c); }
; #pragma unroll
;     for (int c = 0; c < CH; ++c)
; #pragma unroll
;         for (int mi = 0; mi < 4; ++mi)
; #pragma unroll
;             for (int ni = 0; ni < 4; ++ni) acc[mi][ni] = __builtin_amdgcn_mfma_f32_16x16x32_bf16(b[c][ni], a[c][mi], acc[mi][ni], 0, 0, 0);
; }
.LBB0_1385:
	s_add_i32 s1, s0, 16
	s_add_i32 s3, s0, 32
	s_add_i32 s18, s0, 48
	v_mad_i64_i32 v[86:87], s[6:7], s1, v197, v[92:93]
	v_mad_i64_i32 v[174:175], s[6:7], s3, v197, v[92:93]
	v_mad_i64_i32 v[172:173], s[6:7], s18, v197, v[92:93]
	v_mad_i64_i32 v[78:79], s[6:7], s0, v197, v[92:93]
	s_ashr_i32 s1, s0, 31
	s_add_i32 s2, s2, 32
	global_load_dwordx4 v[66:69], v[78:79], off
	global_load_dwordx4 v[70:73], v[86:87], off
	global_load_dwordx4 v[80:83], v[174:175], off
	global_load_dwordx4 v[100:103], v[172:173], off
	global_load_dwordx4 v[104:107], v[90:91], off
	global_load_dwordx4 v[108:111], v[94:95], off
	global_load_dwordx4 v[120:123], v[78:79], off offset:64
	global_load_dwordx4 v[124:127], v[86:87], off offset:64
	global_load_dwordx4 v[128:131], v[174:175], off offset:64
	global_load_dwordx4 v[132:135], v[172:173], off offset:64
	global_load_dwordx4 v[136:139], v[90:91], off offset:64
	global_load_dwordx4 v[152:155], v[94:95], off offset:64
	global_load_dwordx4 v[164:167], v[78:79], off offset:128
	global_load_dwordx4 v[200:203], v[86:87], off offset:128
	global_load_dwordx4 v[204:207], v[174:175], off offset:128
	global_load_dwordx4 v[208:211], v[172:173], off offset:128
	global_load_dwordx4 v[212:215], v[90:91], off offset:128
	global_load_dwordx4 v[216:219], v[94:95], off offset:128
	s_waitcnt vmcnt(12)
	v_mfma_f32_16x16x32_bf16 v[2:5], v[66:69], v[104:107], 0
	v_mfma_f32_16x16x32_bf16 v[6:9], v[70:73], v[104:107], 0
	v_mfma_f32_16x16x32_bf16 v[10:13], v[80:83], v[104:107], 0
	v_mfma_f32_16x16x32_bf16 v[14:17], v[100:103], v[104:107], 0
	v_mfma_f32_16x16x32_bf16 v[18:21], v[66:69], v[108:111], 0
	v_mfma_f32_16x16x32_bf16 v[22:25], v[70:73], v[108:111], 0
	v_mfma_f32_16x16x32_bf16 v[26:29], v[80:83], v[108:111], 0
	v_mfma_f32_16x16x32_bf16 v[30:33], v[100:103], v[108:111], 0
	global_load_dwordx4 v[66:69], v[78:79], off offset:192
	global_load_dwordx4 v[70:73], v[86:87], off offset:192
	global_load_dwordx4 v[80:83], v[174:175], off offset:192
	global_load_dwordx4 v[100:103], v[172:173], off offset:192
	global_load_dwordx4 v[104:107], v[90:91], off offset:192
	global_load_dwordx4 v[108:111], v[94:95], off offset:192
	s_waitcnt vmcnt(12)
	v_mfma_f32_16x16x32_bf16 v[2:5], v[120:123], v[136:139], v[2:5]
	v_mfma_f32_16x16x32_bf16 v[6:9], v[124:127], v[136:139], v[6:9]
	v_mfma_f32_16x16x32_bf16 v[10:13], v[128:131], v[136:139], v[10:13]
	v_mfma_f32_16x16x32_bf16 v[14:17], v[132:135], v[136:139], v[14:17]
	v_mfma_f32_16x16x32_bf16 v[18:21], v[120:123], v[152:155], v[18:21]
	v_mfma_f32_16x16x32_bf16 v[22:25], v[124:127], v[152:155], v[22:25]
	v_mfma_f32_16x16x32_bf16 v[26:29], v[128:131], v[152:155], v[26:29]
	v_mfma_f32_16x16x32_bf16 v[30:33], v[132:135], v[152:155], v[30:33]
	global_load_dwordx4 v[120:123], v[78:79], off offset:256
	global_load_dwordx4 v[124:127], v[86:87], off offset:256
	global_load_dwordx4 v[128:131], v[174:175], off offset:256
	global_load_dwordx4 v[132:135], v[172:173], off offset:256
	global_load_dwordx4 v[136:139], v[90:91], off offset:256
	global_load_dwordx4 v[152:155], v[94:95], off offset:256
	s_waitcnt vmcnt(12)
	v_mfma_f32_16x16x32_bf16 v[2:5], v[164:167], v[212:215], v[2:5]
	v_mfma_f32_16x16x32_bf16 v[6:9], v[200:203], v[212:215], v[6:9]
	v_mfma_f32_16x16x32_bf16 v[10:13], v[204:207], v[212:215], v[10:13]
	v_mfma_f32_16x16x32_bf16 v[14:17], v[208:211], v[212:215], v[14:17]
	v_mfma_f32_16x16x32_bf16 v[18:21], v[164:167], v[216:219], v[18:21]
	v_mfma_f32_16x16x32_bf16 v[22:25], v[200:203], v[216:219], v[22:25]
	v_mfma_f32_16x16x32_bf16 v[26:29], v[204:207], v[216:219], v[26:29]
	v_mfma_f32_16x16x32_bf16 v[30:33], v[208:211], v[216:219], v[30:33]
	global_load_dwordx4 v[164:167], v[78:79], off offset:320
	global_load_dwordx4 v[200:203], v[86:87], off offset:320
	global_load_dwordx4 v[204:207], v[174:175], off offset:320
	global_load_dwordx4 v[208:211], v[172:173], off offset:320
	global_load_dwordx4 v[212:215], v[90:91], off offset:320
	global_load_dwordx4 v[216:219], v[94:95], off offset:320
	s_waitcnt vmcnt(12)
	v_mfma_f32_16x16x32_bf16 v[2:5], v[66:69], v[104:107], v[2:5]
	v_mfma_f32_16x16x32_bf16 v[6:9], v[70:73], v[104:107], v[6:9]
	v_mfma_f32_16x16x32_bf16 v[10:13], v[80:83], v[104:107], v[10:13]
	v_mfma_f32_16x16x32_bf16 v[14:17], v[100:103], v[104:107], v[14:17]
	v_mfma_f32_16x16x32_bf16 v[18:21], v[66:69], v[108:111], v[18:21]
	v_mfma_f32_16x16x32_bf16 v[22:25], v[70:73], v[108:111], v[22:25]
	v_mfma_f32_16x16x32_bf16 v[26:29], v[80:83], v[108:111], v[26:29]
	v_mfma_f32_16x16x32_bf16 v[30:33], v[100:103], v[108:111], v[30:33]
	global_load_dwordx4 v[66:69], v[78:79], off offset:384
	global_load_dwordx4 v[70:73], v[86:87], off offset:384
	global_load_dwordx4 v[80:83], v[174:175], off offset:384
	global_load_dwordx4 v[100:103], v[172:173], off offset:384
	global_load_dwordx4 v[104:107], v[90:91], off offset:384
	global_load_dwordx4 v[108:111], v[94:95], off offset:384
	s_waitcnt vmcnt(12)
	v_mfma_f32_16x16x32_bf16 v[2:5], v[120:123], v[136:139], v[2:5]
	v_mfma_f32_16x16x32_bf16 v[6:9], v[124:127], v[136:139], v[6:9]
	v_mfma_f32_16x16x32_bf16 v[10:13], v[128:131], v[136:139], v[10:13]
	v_mfma_f32_16x16x32_bf16 v[14:17], v[132:135], v[136:139], v[14:17]
	v_mfma_f32_16x16x32_bf16 v[18:21], v[120:123], v[152:155], v[18:21]
	v_mfma_f32_16x16x32_bf16 v[22:25], v[124:127], v[152:155], v[22:25]
	v_mfma_f32_16x16x32_bf16 v[26:29], v[128:131], v[152:155], v[26:29]
	v_mfma_f32_16x16x32_bf16 v[30:33], v[132:135], v[152:155], v[30:33]
	global_load_dwordx4 v[120:123], v[78:79], off offset:448
	global_load_dwordx4 v[124:127], v[86:87], off offset:448
	global_load_dwordx4 v[128:131], v[174:175], off offset:448
	global_load_dwordx4 v[132:135], v[172:173], off offset:448
	global_load_dwordx4 v[136:139], v[90:91], off offset:448
	global_load_dwordx4 v[152:155], v[94:95], off offset:448
	s_waitcnt vmcnt(12)
; #define LAS __attribute__((address_space(3)))
; template <int CH>
; DEV void cg_chunk(f32x4 (&acc)[4][4], const bf16_t* ap, const bf16_t* bp, const int (&brow)[4], int K) {
;     bf16x8 a[CH][4], b[CH][4];
; #pragma unroll
;     for (int c = 0; c < CH; ++c)
; #pragma unroll
;         for (int i = 0; i < 4; ++i) { a[c][i] = *(const bf16x8*)(ap + (size_t)(16 * i) * K + 32 * c); b[c][i] = *(const bf16x8*)(bp + (size_t)brow[i] * K + 32 * c); }
; #pragma unroll
;     for (int c = 0; c < CH; ++c)
; #pragma unroll
;         for (int mi = 0; mi < 4; ++mi)
; #pragma unroll
;             for (int ni = 0; ni < 4; ++ni) acc[mi][ni] = __builtin_amdgcn_mfma_f32_16x16x32_bf16(b[c][ni], a[c][mi], acc[mi][ni], 0, 0, 0);
; }
; template <int MODE>
; DEV void cgemm_tile(const Fr& F, const bf16_t* A, const bf16_t* Bt, int K, int rb, int cb, bf16_t* O, int ldc) {
;     ...
; #pragma unroll
;     for (int mi = 0; mi < 4; ++mi)
; #pragma unroll
;         for (int ni = 0; ni < 4; ++ni) *(LAS f32x4*)(part + (w * 64 + 16 * mi + fr) * 64 + ((16 * ni + 4 * fq) ^ (fr << 2))) = acc[mi][ni];
	v_mfma_f32_16x16x32_bf16 v[2:5], v[164:167], v[212:215], v[2:5]
	v_mfma_f32_16x16x32_bf16 v[6:9], v[200:203], v[212:215], v[6:9]
	v_mfma_f32_16x16x32_bf16 v[10:13], v[204:207], v[212:215], v[10:13]
	v_mfma_f32_16x16x32_bf16 v[14:17], v[208:211], v[212:215], v[14:17]
	v_mfma_f32_16x16x32_bf16 v[18:21], v[164:167], v[216:219], v[18:21]
	v_mfma_f32_16x16x32_bf16 v[22:25], v[200:203], v[216:219], v[22:25]
	v_mfma_f32_16x16x32_bf16 v[26:29], v[204:207], v[216:219], v[26:29]
	v_mfma_f32_16x16x32_bf16 v[30:33], v[208:211], v[216:219], v[30:33]
	global_load_dwordx4 v[164:167], v[78:79], off offset:512
	global_load_dwordx4 v[200:203], v[86:87], off offset:512
	global_load_dwordx4 v[204:207], v[174:175], off offset:512
	global_load_dwordx4 v[208:211], v[172:173], off offset:512
	global_load_dwordx4 v[212:215], v[90:91], off offset:512
	global_load_dwordx4 v[216:219], v[94:95], off offset:512
	s_waitcnt vmcnt(12)
	v_mfma_f32_16x16x32_bf16 v[2:5], v[66:69], v[104:107], v[2:5]
	v_mfma_f32_16x16x32_bf16 v[6:9], v[70:73], v[104:107], v[6:9]
	v_mfma_f32_16x16x32_bf16 v[10:13], v[80:83], v[104:107], v[10:13]
	v_mfma_f32_16x16x32_bf16 v[14:17], v[100:103], v[104:107], v[14:17]
	v_mfma_f32_16x16x32_bf16 v[18:21], v[66:69], v[108:111], v[18:21]
	v_mfma_f32_16x16x32_bf16 v[22:25], v[70:73], v[108:111], v[22:25]
	v_mfma_f32_16x16x32_bf16 v[26:29], v[80:83], v[108:111], v[26:29]
	v_mfma_f32_16x16x32_bf16 v[30:33], v[100:103], v[108:111], v[30:33]
	global_load_dwordx4 v[66:69], v[78:79], off offset:576
	global_load_dwordx4 v[70:73], v[86:87], off offset:576
	global_load_dwordx4 v[80:83], v[174:175], off offset:576
	global_load_dwordx4 v[100:103], v[172:173], off offset:576
	global_load_dwordx4 v[104:107], v[90:91], off offset:576
	global_load_dwordx4 v[108:111], v[94:95], off offset:576
	s_waitcnt vmcnt(12)
	v_mfma_f32_16x16x32_bf16 v[2:5], v[120:123], v[136:139], v[2:5]
	v_mfma_f32_16x16x32_bf16 v[6:9], v[124:127], v[136:139], v[6:9]
	v_mfma_f32_16x16x32_bf16 v[10:13], v[128:131], v[136:139], v[10:13]
	v_mfma_f32_16x16x32_bf16 v[14:17], v[132:135], v[136:139], v[14:17]
	v_mfma_f32_16x16x32_bf16 v[18:21], v[120:123], v[152:155], v[18:21]
	v_mfma_f32_16x16x32_bf16 v[22:25], v[124:127], v[152:155], v[22:25]
	v_mfma_f32_16x16x32_bf16 v[26:29], v[128:131], v[152:155], v[26:29]
	v_mfma_f32_16x16x32_bf16 v[30:33], v[132:135], v[152:155], v[30:33]
	global_load_dwordx4 v[120:123], v[78:79], off offset:640
	global_load_dwordx4 v[124:127], v[86:87], off offset:640
	global_load_dwordx4 v[128:131], v[174:175], off offset:640
	global_load_dwordx4 v[132:135], v[172:173], off offset:640
	global_load_dwordx4 v[136:139], v[90:91], off offset:640
	global_load_dwordx4 v[152:155], v[94:95], off offset:640
	s_waitcnt vmcnt(12)
	v_mfma_f32_16x16x32_bf16 v[2:5], v[164:167], v[212:215], v[2:5]
	v_mfma_f32_16x16x32_bf16 v[6:9], v[200:203], v[212:215], v[6:9]
	v_mfma_f32_16x16x32_bf16 v[10:13], v[204:207], v[212:215], v[10:13]
	v_mfma_f32_16x16x32_bf16 v[14:17], v[208:211], v[212:215], v[14:17]
	v_mfma_f32_16x16x32_bf16 v[18:21], v[164:167], v[216:219], v[18:21]
	v_mfma_f32_16x16x32_bf16 v[22:25], v[200:203], v[216:219], v[22:25]
	v_mfma_f32_16x16x32_bf16 v[26:29], v[204:207], v[216:219], v[26:29]
	v_mfma_f32_16x16x32_bf16 v[30:33], v[208:211], v[216:219], v[30:33]
	s_waitcnt vmcnt(6)
	v_mfma_f32_16x16x32_bf16 v[2:5], v[66:69], v[104:107], v[2:5]
	v_mfma_f32_16x16x32_bf16 v[6:9], v[70:73], v[104:107], v[6:9]
	v_mfma_f32_16x16x32_bf16 v[10:13], v[80:83], v[104:107], v[10:13]
	v_mfma_f32_16x16x32_bf16 v[14:17], v[100:103], v[104:107], v[14:17]
	v_mfma_f32_16x16x32_bf16 v[18:21], v[66:69], v[108:111], v[18:21]
	v_mfma_f32_16x16x32_bf16 v[22:25], v[70:73], v[108:111], v[22:25]
	v_mfma_f32_16x16x32_bf16 v[26:29], v[80:83], v[108:111], v[26:29]
	v_mfma_f32_16x16x32_bf16 v[30:33], v[100:103], v[108:111], v[30:33]
	s_waitcnt vmcnt(0)
	v_mfma_f32_16x16x32_bf16 v[2:5], v[120:123], v[136:139], v[2:5]
	v_mfma_f32_16x16x32_bf16 v[6:9], v[124:127], v[136:139], v[6:9]
	v_mfma_f32_16x16x32_bf16 v[10:13], v[128:131], v[136:139], v[10:13]
	v_mfma_f32_16x16x32_bf16 v[14:17], v[132:135], v[136:139], v[14:17]
	v_mfma_f32_16x16x32_bf16 v[18:21], v[120:123], v[152:155], v[18:21]
	v_mfma_f32_16x16x32_bf16 v[22:25], v[124:127], v[152:155], v[22:25]
	v_mfma_f32_16x16x32_bf16 v[26:29], v[128:131], v[152:155], v[26:29]
	v_mfma_f32_16x16x32_bf16 v[30:33], v[132:135], v[152:155], v[30:33]
	s_nop 7
	ds_write_b128 v176, v[2:5]
	ds_write_b128 v177, v[6:9]
	ds_write_b128 v178, v[10:13]
	ds_write_b128 v179, v[14:17]
	ds_write_b128 v176, v[18:21] offset:4096
	ds_write_b128 v177, v[22:25] offset:4096
	ds_write_b128 v178, v[26:29] offset:4096
	ds_write_b128 v179, v[30:33] offset:4096
	s_waitcnt lgkmcnt(0)
	s_barrier
; #define LAS __attribute__((address_space(3)))
; DEV unsigned pk2(float lo, float hi) { unsigned r; asm("v_cvt_pk_bf16_f32 %0, %1, %2" : "=v"(r) : "v"(lo), "v"(hi)); return r; }
; template <int MODE>
; DEV void cgemm_tile(const Fr& F, const bf16_t* A, const bf16_t* Bt, int K, int rb, int cb, bf16_t* O, int ldc) {
;     ...
;     __syncthreads();
;     { const int row = F.tid >> 3, c8 = (F.tid & 7) * 8, sw = (row & 15) << 2;
;       if (MODE == 0) {
;           f32x4 s0 = (f32x4){0.f, 0.f, 0.f, 0.f}, s1 = s0;
; #pragma unroll
;           for (int ww = 0; ww < 8; ++ww) { s0 += *(const LAS f32x4*)(part + (ww * 64 + row) * 64 + (c8 ^ sw)); s1 += *(const LAS f32x4*)(part + (ww * 64 + row) * 64 + ((c8 + 4) ^ sw)); }
;           u32x4 o; o.x = pk2(s0[0], s0[1]); o.y = pk2(s0[2], s0[3]); o.z = pk2(s1[0], s1[1]); o.w = pk2(s1[2], s1[3]);
;           *(u32x4*)(O + (size_t)(arow0 + row) * ldc + cb * 64 + c8) = o;
	v_readlane_b32 s3, v240, 47
	s_lshr_b32 s6, s15, 2
	s_lshr_b32 s3, s3, 10
	s_cmp_lg_u32 s3, s6
	s_cbranch_scc1 .Lcg8h_skip
	ds_read_b128 v[2:5], v180
	ds_read_b128 v[6:9], v180 offset:16384
	ds_read_b128 v[10:13], v181
	ds_read_b128 v[14:17], v181 offset:16384
	ds_read_b128 v[18:21], v180 offset:32768
	ds_read_b128 v[22:25], v180 offset:49152
	ds_read_b128 v[26:29], v181 offset:32768
	ds_read_b128 v[30:33], v181 offset:49152
	ds_read_b128 v[34:37], v182
	ds_read_b128 v[38:41], v183
	ds_read_b128 v[42:45], v184
	ds_read_b128 v[46:49], v185
	ds_read_b128 v[50:53], v186
	ds_read_b128 v[54:57], v187
	ds_read_b128 v[58:61], v198
	ds_read_b128 v[62:65], v199
	s_waitcnt lgkmcnt(14)
	v_pk_add_f32 v[4:5], v[4:5], 0 op_sel_hi:[1,0]
	v_pk_add_f32 v[2:3], v[2:3], 0 op_sel_hi:[1,0]
	s_waitcnt lgkmcnt(13)
	v_pk_add_f32 v[12:13], v[12:13], 0 op_sel_hi:[1,0]
	v_pk_add_f32 v[10:11], v[10:11], 0 op_sel_hi:[1,0]
	v_pk_add_f32 v[4:5], v[4:5], v[8:9]
	v_pk_add_f32 v[2:3], v[2:3], v[6:7]
	s_waitcnt lgkmcnt(12)
	v_pk_add_f32 v[6:7], v[12:13], v[16:17]
	v_pk_add_f32 v[8:9], v[10:11], v[14:15]
	s_waitcnt lgkmcnt(11)
	v_pk_add_f32 v[4:5], v[4:5], v[20:21]
	v_pk_add_f32 v[2:3], v[2:3], v[18:19]
	s_waitcnt lgkmcnt(9)
	v_pk_add_f32 v[6:7], v[6:7], v[28:29]
	v_pk_add_f32 v[8:9], v[8:9], v[26:27]
	v_pk_add_f32 v[4:5], v[4:5], v[24:25]
	v_pk_add_f32 v[2:3], v[2:3], v[22:23]
	s_waitcnt lgkmcnt(8)
	v_pk_add_f32 v[6:7], v[6:7], v[32:33]
	v_pk_add_f32 v[8:9], v[8:9], v[30:31]
	s_waitcnt lgkmcnt(7)
	v_pk_add_f32 v[4:5], v[4:5], v[36:37]
	v_pk_add_f32 v[2:3], v[2:3], v[34:35]
	s_waitcnt lgkmcnt(6)
	v_pk_add_f32 v[6:7], v[6:7], v[40:41]
	v_pk_add_f32 v[8:9], v[8:9], v[38:39]
	s_waitcnt lgkmcnt(5)
	v_pk_add_f32 v[4:5], v[4:5], v[44:45]
	v_pk_add_f32 v[2:3], v[2:3], v[42:43]
	v_lshl_add_u64 v[70:71], s[0:1], 1, v[170:171]
	s_addk_i32 s0, 0x800
	s_waitcnt lgkmcnt(4)
	v_pk_add_f32 v[6:7], v[6:7], v[48:49]
	v_pk_add_f32 v[8:9], v[8:9], v[46:47]
	s_waitcnt lgkmcnt(3)
	v_pk_add_f32 v[4:5], v[4:5], v[52:53]
	v_pk_add_f32 v[2:3], v[2:3], v[50:51]
	s_cmpk_gt_i32 s2, 0xffef
	s_waitcnt lgkmcnt(2)
	v_pk_add_f32 v[6:7], v[6:7], v[56:57]
	v_pk_add_f32 v[8:9], v[8:9], v[54:55]
	s_waitcnt lgkmcnt(1)
	v_pk_add_f32 v[4:5], v[4:5], v[60:61]
	v_pk_add_f32 v[2:3], v[2:3], v[58:59]
	s_waitcnt lgkmcnt(0)
	v_pk_add_f32 v[6:7], v[6:7], v[64:65]
	v_pk_add_f32 v[8:9], v[8:9], v[62:63]
	v_cvt_pk_bf16_f32 v2, v2, v3
	v_cvt_pk_bf16_f32 v3, v4, v5
	v_cvt_pk_bf16_f32 v5, v6, v7
	s_nop 0
	v_cvt_pk_bf16_f32 v4, v8, v9
	global_store_dwordx4 v[70:71], v[2:5], off
.Lcg8h_skip:
	s_barrier
	s_cbranch_scc0 .LBB0_1385
